# attention unit K/V first-tile loads issued at unit start; conversion loads as dwordx2
# baseline (speedup 1.0000x reference)
; __device__ __forceinline__ void attn_unit(CArgs a, int layer, int unit, LAS unsigned char* lds) {
;     const int tid = ltid(), lane = tid & 63, wid = tid >> 6, r32 = lane & 31, hi = lane >> 5;
;     const unsigned char* WSB = a->ws;
;     const int qb = unit & 7, bh = unit >> 3, h = bh & 7, b = bh >> 3;
;     const bf16_t* Kg = (const bf16_t*)(a->ws + WS_KF) + (size_t)bh * SEQ * 96;
;     const bf16_t* Vg = (const bf16_t*)(a->ws + WS_VT) + (size_t)bh * SEQ * 64;
;     const float2* cst = (const float2*)(a->ws + WS_CS);
;     const float* qhn = a->mla_qhn + layer * 96;
;     LAS float* wsf = (LAS float*)(lds + AT_WS) + wid * 64;
;     const int qrow = b * SEQ + qb * 256 + wid * 32 + r32;
;     bf16x8 qf[6]; float mref;
;     {
;         const bf16_t* qp = (const bf16_t*)(a->ws + WS_QR) + (size_t)qrow * 768 + h * 96;
;         float q[6][8]; float ss = 0.f;
; #pragma unroll
;         for (int s = 0; s < 6; ++s) { unpack8(*(const u32x4*)(qp + 16 * s + 8 * hi), q[s]);
; #pragma unroll
;             for (int e = 0; e < 8; ++e) ss += q[s][e] * q[s][e]; }
;         ss += __shfl_xor(ss, 32);
;         const float rq = rsqrtf(ss * (1.f / 96.f) + EPS);
; #pragma unroll
;         for (int s = 0; s < 6; ++s)
; #pragma unroll
;             for (int e = 0; e < 8; ++e) q[s][e] *= rq * qhn[16 * s + 8 * hi + e];
; #pragma unroll
;         for (int e = 0; e < 8; ++e) { const float2 c = cst[(size_t)qrow * 16 + 8 * hi + e]; const float x1 = q[4][e], x2 = q[5][e];
;             q[4][e] = x1 * c.x - x2 * c.y; q[5][e] = x1 * c.y + x2 * c.x; }
;         float qn2 = 0.f;
; #pragma unroll
;         for (int s = 0; s < 6; ++s) {
; #pragma unroll
;             for (int e = 0; e < 8; ++e) { q[s][e] *= QK_SCALE; qn2 += q[s][e] * q[s][e]; }
;             qf[s] = __builtin_bit_cast(bf16x8, pack8(q[s]));
;         }
;         qn2 += __shfl_xor(qn2, 32);
;         const float* khn = a->mla_khn + layer * 96;
;         float gm = fmaxf(fabsf(khn[lane]), fabsf(khn[64 + (lane & 31)]));
; #pragma unroll
;         for (int o = 1; o < 64; o <<= 1) gm = fmaxf(gm, __shfl_xor(gm, o));
;         mref = 1.02f * sqrtf(qn2) * 9.797958971f * gm;
;     }
;     u32x4 kr0, kr1, vr;
;     const int kc0 = tid, kc1 = tid + 512;
;     constexpr int NT = SEQ / 64;
;     auto gloadK = [&](int t) {
;         const bf16_t* kt = Kg + (size_t)t * 64 * 96;
;         kr0 = *(const u32x4*)(kt + kc0 * 8);
.LBB0_66:
	s_lshl_b32 s2, s10, 1
	v_mov_b32_e32 v159, v244
	s_and_b32 s2, s2, 0x1fe
	s_ashr_i32 s3, s10, 8
	s_load_dwordx2 s[60:61], s[6:7], 0xe8
	s_load_dwordx4 s[40:43], s[6:7], 0x90
	s_add_i32 s12, s2, s3
	s_ashr_i32 s2, s12, 3
	s_ashr_i32 s3, s2, 31
	s_and_b32 s11, s2, 7
	s_lshl_b64 s[22:23], s[2:3], 18
	s_waitcnt lgkmcnt(0)
	s_add_u32 s3, s60, s22
	s_addc_u32 s13, s61, s23
	s_add_u32 s18, s3, 0x17a00000
	s_addc_u32 s19, s13, 0
	s_lshl_b32 s3, s12, 5
	s_lshl_b32 s12, s12, 8
	s_and_b32 s3, s3, 0xfffff800
	s_and_b32 s12, s12, 0x700
	v_ashrrev_i32_e32 v0, 1, v159
	s_or_b32 s3, s3, s12
	v_and_b32_e32 v162, 0xffffffe0, v0
	v_and_b32_e32 v161, 31, v159
	v_add_u32_e32 v158, s3, v162
	v_or_b32_e32 v2, v158, v161
	v_mov_b64_e32 v[4:5], s[60:61]
	s_movk_i32 s3, 0x600
	v_mad_i64_i32 v[4:5], s[12:13], v2, s3, v[4:5]
	s_mul_hi_i32 s3, s2, 0x60000
	s_mul_i32 s2, s2, 0x60000
	s_add_u32 s2, s60, s2
	v_bfe_u32 v160, v159, 5, 1
	s_mul_i32 s34, s11, 0xc0
	v_ashrrev_i32_e32 v3, 31, v2
	s_addc_u32 s3, s61, s3
	v_lshl_add_u64 v[4:5], v[4:5], 0, s[34:35]
	v_lshlrev_b32_e32 v0, 4, v160
	v_lshlrev_b64 v[2:3], 7, v[2:3]
	s_add_u32 s20, s2, 0x16200000
	v_lshl_add_u64 v[14:15], v[4:5], 0, v[0:1]
	s_mov_b64 s[12:13], 0x14a00000
	v_lshl_add_u64 v[2:3], s[60:61], 0, v[2:3]
	v_lshlrev_b32_e32 v0, 6, v160
	s_addc_u32 s21, s3, 0
	v_lshlrev_b32_e32 v236, 4, v159
	v_add_u32_e32 v237, 0x200, v159
	v_min_i32_e32 v237, 0x2ff, v237
	v_lshlrev_b32_e32 v237, 4, v237
	s_add_u32 s26, s20, 0x3000
	s_addc_u32 s27, s21, 0
	global_load_dwordx4 v[204:207], v236, s[20:21]
	global_load_dwordx4 v[208:211], v236, s[18:19]
	global_load_dwordx4 v[224:227], v237, s[20:21]
	global_load_dwordx4 v[228:231], v236, s[26:27]
	global_load_dwordx4 v[232:235], v237, s[26:27]
	v_lshl_add_u64 v[16:17], v[14:15], 0, s[12:13]
	v_lshl_add_u64 v[26:27], v[2:3], 0, v[0:1]
	s_mov_b64 s[12:13], 0x200000
	s_add_u32 s24, s40, s16
	v_lshl_add_u64 v[10:11], v[26:27], 0, s[12:13]
	s_addc_u32 s25, s41, s17
	v_and_b32_e32 v49, 32, v159
	global_load_dwordx4 v[50:53], v[16:17], off offset:128
	global_load_dwordx4 v[54:57], v[16:17], off offset:160
	global_load_dwordx4 v[6:9], v[10:11], off offset:16
	global_load_dwordx4 v[2:5], v[10:11], off offset:48
	s_nop 0
	global_load_dwordx4 v[10:13], v[10:11], off offset:32
	s_nop 0
	global_load_dwordx4 v[18:21], v49, s[24:25] offset:320
	global_load_dwordx4 v[58:61], v[16:17], off offset:96
	global_load_dwordx4 v[62:65], v[16:17], off offset:64
	v_and_b32_e32 v0, 64, v247
	v_xor_b32_e32 v22, 32, v247
	v_add_u32_e32 v48, 64, v0
	v_cmp_lt_i32_e32 vcc, v22, v48
	s_mov_b32 s2, 0x14a00000
	global_load_dwordx4 v[66:69], v[16:17], off offset:32
	v_cndmask_b32_e32 v16, v247, v22, vcc
	v_add_co_u32_e32 v14, vcc, s2, v14
	s_mov_b32 s2, 0x200000
	s_nop 0
	v_addc_co_u32_e32 v15, vcc, 0, v15, vcc
	global_load_dwordx4 v[70:73], v[14:15], off
	global_load_dwordx4 v[22:25], v49, s[24:25] offset:336
	v_add_co_u32_e32 v14, vcc, s2, v26
	v_lshlrev_b32_e32 v164, 2, v16
	s_nop 0
	v_addc_co_u32_e32 v15, vcc, 0, v27, vcc
	global_load_dwordx4 v[30:33], v49, s[24:25] offset:272
	global_load_dwordx4 v[26:29], v49, s[24:25] offset:256
	s_nop 0
	global_load_dwordx4 v[14:17], v[14:15], off
	v_and_b32_e32 v0, 63, v159
	s_add_u32 s2, s42, s16
	s_addc_u32 s3, s43, s17
	v_lshlrev_b32_e32 v165, 2, v161
	s_waitcnt vmcnt(13)
	v_lshlrev_b32_e32 v38, 16, v53
	v_and_b32_e32 v39, 0xffff0000, v53
	s_waitcnt vmcnt(12)
	v_lshlrev_b32_e32 v36, 16, v57
	v_and_b32_e32 v37, 0xffff0000, v57
	v_lshlrev_b32_e32 v44, 16, v52
	v_and_b32_e32 v45, 0xffff0000, v52
	v_lshlrev_b32_e32 v40, 16, v56
	v_and_b32_e32 v41, 0xffff0000, v56
	v_lshlrev_b32_e32 v46, 16, v51
	s_waitcnt vmcnt(10)
	v_mov_b32_e32 v34, v2
	v_mov_b32_e32 v35, v4
	v_mov_b32_e32 v4, v3
	s_waitcnt vmcnt(9)
	v_mov_b32_e32 v2, v10
	v_mov_b32_e32 v3, v12
	v_mov_b32_e32 v12, v11
	v_and_b32_e32 v11, 0xffff0000, v55
	v_and_b32_e32 v10, 16, v51
	v_lshlrev_b32_e32 v98, 16, v55
	v_and_b32_e32 v99, 0xffff0000, v51
	v_lshlrev_b32_e32 v102, 16, v50
	v_and_b32_e32 v103, 0xffff0000, v50
	v_lshlrev_b32_e32 v106, 16, v54
	v_and_b32_e32 v107, 0xffff0000, v54
	s_waitcnt vmcnt(7)
	v_lshlrev_b32_e32 v110, 16, v61
	v_and_b32_e32 v111, 0xffff0000, v61
	global_load_dwordx4 v[50:53], v49, s[24:25] offset:208
	global_load_dwordx4 v[54:57], v49, s[24:25] offset:192
	v_lshlrev_b32_e32 v114, 16, v60
	v_and_b32_e32 v115, 0xffff0000, v60
	v_lshlrev_b32_e32 v118, 16, v59
	v_and_b32_e32 v119, 0xffff0000, v59
	v_lshlrev_b32_e32 v122, 16, v58
	v_and_b32_e32 v123, 0xffff0000, v58
	s_waitcnt vmcnt(8)
	v_lshlrev_b32_e32 v126, 16, v65
	v_and_b32_e32 v127, 0xffff0000, v65
	global_load_dwordx4 v[58:61], v49, s[24:25] offset:144
	global_load_dwordx4 v[74:77], v49, s[24:25] offset:128
	v_lshlrev_b32_e32 v130, 16, v64
	v_and_b32_e32 v131, 0xffff0000, v64
	v_lshlrev_b32_e32 v134, 16, v63
	v_and_b32_e32 v135, 0xffff0000, v63
	v_lshlrev_b32_e32 v138, 16, v62
	v_and_b32_e32 v139, 0xffff0000, v62
	global_load_dwordx4 v[62:65], v49, s[24:25] offset:80
	global_load_dwordx4 v[78:81], v49, s[24:25] offset:64
	global_load_dwordx4 v[82:85], v49, s[24:25] offset:16
	global_load_dwordx4 v[86:89], v49, s[24:25]
	s_waitcnt vmcnt(12)
; __device__ __forceinline__ void attn_unit(CArgs a, int layer, int unit, LAS unsigned char* lds) {
;     ...
;         const bf16_t* qp = (const bf16_t*)(a->ws + WS_QR) + (size_t)qrow * 768 + h * 96;
;         float q[6][8]; float ss = 0.f;
; #pragma unroll
;         for (int s = 0; s < 6; ++s) { unpack8(*(const u32x4*)(qp + 16 * s + 8 * hi), q[s]);
; #pragma unroll
;             for (int e = 0; e < 8; ++e) ss += q[s][e] * q[s][e]; }
;         ss += __shfl_xor(ss, 32);
;         const float rq = rsqrtf(ss * (1.f / 96.f) + EPS);
; #pragma unroll
;         for (int s = 0; s < 6; ++s)
; #pragma unroll
;             for (int e = 0; e < 8; ++e) q[s][e] *= rq * qhn[16 * s + 8 * hi + e];
; #pragma unroll
	v_lshlrev_b32_e32 v172, 16, v70
	v_and_b32_e32 v173, 0xffff0000, v70
	v_lshlrev_b32_e32 v168, 16, v71
	v_and_b32_e32 v169, 0xffff0000, v71
	v_pk_mul_f32 v[70:71], v[172:173], v[172:173]
	v_mov_b32_e32 v100, v20
	v_pk_mul_f32 v[170:171], v[168:169], v[168:169]
	v_add_f32_e32 v20, v70, v71
	v_lshlrev_b32_e32 v166, 16, v72
	v_and_b32_e32 v167, 0xffff0000, v72
	v_add_f32_e32 v20, v170, v20
	v_lshlrev_b32_e32 v154, 16, v73
	v_and_b32_e32 v155, 0xffff0000, v73
	v_pk_mul_f32 v[72:73], v[166:167], v[166:167]
	v_add_f32_e32 v20, v171, v20
	v_add_f32_e32 v20, v72, v20
	v_pk_mul_f32 v[156:157], v[154:155], v[154:155]
	v_add_f32_e32 v20, v73, v20
	v_lshlrev_b32_e32 v152, 16, v66
	v_and_b32_e32 v153, 0xffff0000, v66
	v_add_f32_e32 v20, v156, v20
	v_lshlrev_b32_e32 v148, 16, v67
	v_and_b32_e32 v149, 0xffff0000, v67
	v_pk_mul_f32 v[66:67], v[152:153], v[152:153]
	v_add_f32_e32 v20, v157, v20
	v_add_f32_e32 v20, v66, v20
	v_pk_mul_f32 v[150:151], v[148:149], v[148:149]
	v_add_f32_e32 v20, v67, v20
	v_lshlrev_b32_e32 v146, 16, v68
	v_and_b32_e32 v147, 0xffff0000, v68
	v_add_f32_e32 v20, v150, v20
	v_lshlrev_b32_e32 v142, 16, v69
	v_and_b32_e32 v143, 0xffff0000, v69
	v_pk_mul_f32 v[68:69], v[146:147], v[146:147]
	v_add_f32_e32 v20, v151, v20
	v_add_f32_e32 v20, v68, v20
	v_pk_mul_f32 v[144:145], v[142:143], v[142:143]
	v_add_f32_e32 v20, v69, v20
	v_add_f32_e32 v20, v144, v20
	v_pk_mul_f32 v[140:141], v[138:139], v[138:139]
	v_add_f32_e32 v20, v145, v20
	v_add_f32_e32 v20, v140, v20
	v_pk_mul_f32 v[136:137], v[134:135], v[134:135]
	v_add_f32_e32 v20, v141, v20
	v_add_f32_e32 v20, v136, v20
	v_pk_mul_f32 v[132:133], v[130:131], v[130:131]
	v_add_f32_e32 v20, v137, v20
	v_add_f32_e32 v20, v132, v20
	v_pk_mul_f32 v[128:129], v[126:127], v[126:127]
	v_add_f32_e32 v20, v133, v20
	v_add_f32_e32 v20, v128, v20
	v_pk_mul_f32 v[124:125], v[122:123], v[122:123]
	v_add_f32_e32 v20, v129, v20
	v_add_f32_e32 v20, v124, v20
	v_pk_mul_f32 v[120:121], v[118:119], v[118:119]
	v_add_f32_e32 v20, v125, v20
	v_add_f32_e32 v20, v120, v20
	v_pk_mul_f32 v[116:117], v[114:115], v[114:115]
	v_add_f32_e32 v20, v121, v20
	v_add_f32_e32 v20, v116, v20
	v_pk_mul_f32 v[112:113], v[110:111], v[110:111]
	v_add_f32_e32 v20, v117, v20
	v_add_f32_e32 v20, v112, v20
	v_pk_mul_f32 v[104:105], v[102:103], v[102:103]
	v_add_f32_e32 v20, v113, v20
	v_add_f32_e32 v20, v104, v20
	v_add_f32_e32 v20, v105, v20
	v_fmac_f32_e32 v20, v46, v46
	v_pk_mul_f32 v[94:95], v[44:45], v[44:45]
	v_fmac_f32_e32 v20, v99, v99
	v_add_f32_e32 v20, v94, v20
	v_pk_mul_f32 v[90:91], v[38:39], v[38:39]
	v_add_f32_e32 v20, v95, v20
	v_add_f32_e32 v20, v90, v20
	v_pk_mul_f32 v[108:109], v[106:107], v[106:107]
	v_add_f32_e32 v20, v91, v20
	v_mov_b32_e32 v47, v11
	v_pk_mov_b32 v[10:11], v[10:11], v[98:99] op_sel:[1,0]
	v_add_f32_e32 v20, v108, v20
	v_pk_mul_f32 v[10:11], v[10:11], v[10:11]
	v_add_f32_e32 v20, v109, v20
	v_add_f32_e32 v11, v11, v20
	v_pk_mul_f32 v[96:97], v[40:41], v[40:41]
	v_add_f32_e32 v10, v10, v11
	v_add_f32_e32 v10, v96, v10
	v_pk_mul_f32 v[92:93], v[36:37], v[36:37]
	v_add_f32_e32 v10, v97, v10
	v_add_f32_e32 v10, v92, v10
	v_add_f32_e32 v20, v93, v10
	ds_bpermute_b32 v49, v164, v20
	s_waitcnt vmcnt(9)
	v_mov_b32_e32 v101, v29
	v_mov_b32_e32 v29, v21
	s_waitcnt vmcnt(8)
	v_mov_b32_e32 v66, v14
	v_mov_b32_e32 v67, v16
	s_waitcnt lgkmcnt(0)
	v_add_f32_e32 v20, v20, v49
	v_fmamk_f32 v20, v20, 0x3c2aaaab, v245
	v_mul_f32_e32 v21, 0x4b800000, v20
	v_cmp_gt_f32_e32 vcc, s83, v20
	v_mov_b32_e32 v16, v15
	v_mov_b32_e32 v10, v6
	v_cndmask_b32_e32 v20, v20, v21, vcc
	v_rsq_f32_e32 v20, v20
	v_mov_b32_e32 v11, v9
	v_mov_b32_e32 v42, v7
	v_mov_b32_e32 v43, v8
	v_mul_f32_e32 v14, 0x45800000, v20
	v_cndmask_b32_e32 v14, v20, v14, vcc
	v_pk_mul_f32 v[26:27], v[26:27], v[14:15] op_sel_hi:[1,0]
	s_waitcnt vmcnt(0)
	v_pk_mul_f32 v[20:21], v[86:87], v[14:15] op_sel_hi:[1,0]
	v_pk_mul_f32 v[52:53], v[52:53], v[14:15] op_sel_hi:[1,0]
	v_pk_mul_f32 v[86:87], v[26:27], v[102:103]
	v_pk_mul_f32 v[26:27], v[30:31], v[14:15] op_sel_hi:[1,0]
	v_lshlrev_b32_e32 v30, 2, v0
	v_pk_mul_f32 v[52:53], v[52:53], v[110:111]
	global_load_dword v49, v30, s[2:3]
	global_load_dword v110, v165, s[2:3] offset:256
	v_pk_mul_f32 v[18:19], v[18:19], v[14:15] op_sel_hi:[1,0]
	v_pk_mul_f32 v[68:69], v[88:89], v[14:15] op_sel_hi:[1,0]
	v_pk_mul_f32 v[88:89], v[18:19], v[106:107]
	v_pk_mul_f32 v[18:19], v[100:101], v[14:15] op_sel_hi:[1,0]
	v_pk_mul_f32 v[70:71], v[82:83], v[14:15] op_sel_hi:[1,0]
	v_pk_mul_f32 v[96:97], v[18:19], v[98:99]
	v_pk_mul_f32 v[18:19], v[28:29], v[14:15] op_sel_hi:[1,0]
	v_pk_mul_f32 v[72:73], v[84:85], v[14:15] op_sel_hi:[1,0]
	v_pk_mul_f32 v[78:79], v[78:79], v[14:15] op_sel_hi:[1,0]
	v_pk_mul_f32 v[80:81], v[80:81], v[14:15] op_sel_hi:[1,0]
	v_pk_mul_f32 v[62:63], v[62:63], v[14:15] op_sel_hi:[1,0]
	v_pk_mul_f32 v[64:65], v[64:65], v[14:15] op_sel_hi:[1,0]
	v_pk_mul_f32 v[74:75], v[74:75], v[14:15] op_sel_hi:[1,0]
	v_pk_mul_f32 v[76:77], v[76:77], v[14:15] op_sel_hi:[1,0]
	v_pk_mul_f32 v[58:59], v[58:59], v[14:15] op_sel_hi:[1,0]
	v_pk_mul_f32 v[60:61], v[60:61], v[14:15] op_sel_hi:[1,0]
	v_pk_mul_f32 v[54:55], v[54:55], v[14:15] op_sel_hi:[1,0]
	v_pk_mul_f32 v[56:57], v[56:57], v[14:15] op_sel_hi:[1,0]
	v_pk_mul_f32 v[50:51], v[50:51], v[14:15] op_sel_hi:[1,0]
	v_pk_mul_f32 v[44:45], v[26:27], v[44:45]
	v_pk_mul_f32 v[26:27], v[32:33], v[14:15] op_sel_hi:[1,0]
	v_pk_mul_f32 v[46:47], v[18:19], v[46:47]
	v_pk_mul_f32 v[18:19], v[22:23], v[14:15] op_sel_hi:[1,0]
	v_pk_mul_f32 v[14:15], v[24:25], v[14:15] op_sel_hi:[1,0]
	v_pk_mul_f32 v[10:11], v[10:11], v[96:97]
	v_pk_mul_f32 v[36:37], v[14:15], v[36:37]
; __device__ __forceinline__ u32x4 pack8(const float (&f)[8]) { u32x4 v; v.x = cvt_pk_bf16(f[0], f[1]); v.y = cvt_pk_bf16(f[2], f[3]); v.z = cvt_pk_bf16(f[4], f[5]); v.w = cvt_pk_bf16(f[6], f[7]); return v; }
; __device__ __forceinline__ void attn_unit(CArgs a, int layer, int unit, LAS unsigned char* lds) {
;     ...
;             for (int e = 0; e < 8; ++e) q[s][e] *= rq * qhn[16 * s + 8 * hi + e];
; #pragma unroll
;         for (int e = 0; e < 8; ++e) { const float2 c = cst[(size_t)qrow * 16 + 8 * hi + e]; const float x1 = q[4][e], x2 = q[5][e];
;             q[4][e] = x1 * c.x - x2 * c.y; q[5][e] = x1 * c.y + x2 * c.x; }
;         float qn2 = 0.f;
; #pragma unroll
;         for (int s = 0; s < 6; ++s) {
; #pragma unroll
;             for (int e = 0; e < 8; ++e) { q[s][e] *= QK_SCALE; qn2 += q[s][e] * q[s][e]; }
;             qf[s] = __builtin_bit_cast(bf16x8, pack8(q[s]));
;         }
;         qn2 += __shfl_xor(qn2, 32);
;         const float* khn = a->mla_khn + layer * 96;
;         float gm = fmaxf(fabsf(khn[lane]), fabsf(khn[64 + (lane & 31)]));
; #pragma unroll
;         for (int o = 1; o < 64; o <<= 1) gm = fmaxf(gm, __shfl_xor(gm, o));
;         mref = 1.02f * sqrtf(qn2) * 9.797958971f * gm;
	v_pk_mul_f32 v[14:15], v[66:67], v[88:89]
	v_pk_fma_f32 v[42:43], v[42:43], v[46:47], v[10:11]
	v_pk_fma_f32 v[102:103], v[16:17], v[86:87], v[14:15]
	v_pk_mul_f32 v[16:17], v[16:17], v[88:89]
	v_mov_b32_e32 v88, v46
	v_pk_fma_f32 v[16:17], v[66:67], v[86:87], v[16:17] neg_lo:[0,0,1] neg_hi:[0,0,1]
	v_mov_b32_e32 v87, v97
	v_mov_b32_e32 v46, v7
	v_mov_b32_e32 v97, v9
	v_mov_b32_e32 v86, v6
	v_mov_b32_e32 v89, v8
	v_pk_mul_f32 v[6:7], v[46:47], v[96:97]
	v_pk_mul_f32 v[40:41], v[18:19], v[40:41]
	v_pk_fma_f32 v[6:7], v[86:87], v[88:89], v[6:7] neg_lo:[0,0,1] neg_hi:[0,0,1]
	v_pk_mul_f32 v[10:11], v[44:45], v[12:13]
	v_pk_mul_f32 v[86:87], v[6:7], s[30:31] op_sel_hi:[1,0]
	v_pk_mul_f32 v[6:7], v[40:41], v[12:13]
	v_pk_mul_f32 v[20:21], v[20:21], v[172:173]
	v_pk_fma_f32 v[104:105], v[40:41], v[2:3], v[10:11]
	v_pk_fma_f32 v[2:3], v[44:45], v[2:3], v[6:7] neg_lo:[0,0,1] neg_hi:[0,0,1]
	v_pk_mul_f32 v[68:69], v[68:69], v[168:169]
	v_pk_mul_f32 v[38:39], v[26:27], v[38:39]
	v_pk_mul_f32 v[22:23], v[20:21], s[30:31] op_sel_hi:[1,0]
	v_pk_mul_f32 v[96:97], v[2:3], s[30:31] op_sel_hi:[1,0]
	v_pk_mul_f32 v[2:3], v[36:37], v[4:5]
	v_pk_mul_f32 v[108:109], v[22:23], v[22:23]
	v_pk_mul_f32 v[24:25], v[68:69], s[30:31] op_sel_hi:[1,0]
	v_pk_fma_f32 v[2:3], v[38:39], v[34:35], v[2:3] neg_lo:[0,0,1] neg_hi:[0,0,1]
	v_pk_mul_f32 v[70:71], v[70:71], v[166:167]
	v_pk_mul_f32 v[68:69], v[24:25], v[24:25]
	v_pk_mul_f32 v[100:101], v[2:3], s[30:31] op_sel_hi:[1,0]
	v_add_f32_e32 v2, v108, v109
	v_pk_mul_f32 v[26:27], v[70:71], s[30:31] op_sel_hi:[1,0]
	v_add_f32_e32 v2, v68, v2
	v_pk_mul_f32 v[72:73], v[72:73], v[154:155]
	v_pk_mul_f32 v[70:71], v[26:27], v[26:27]
	v_add_f32_e32 v2, v69, v2
	v_pk_mul_f32 v[28:29], v[72:73], s[30:31] op_sel_hi:[1,0]
	v_add_f32_e32 v2, v70, v2
	v_pk_mul_f32 v[78:79], v[78:79], v[152:153]
	v_pk_mul_f32 v[10:11], v[38:39], v[4:5]
	v_pk_mul_f32 v[72:73], v[28:29], v[28:29]
	v_add_f32_e32 v2, v71, v2
	v_pk_fma_f32 v[106:107], v[36:37], v[34:35], v[10:11]
	v_pk_mul_f32 v[10:11], v[78:79], s[30:31] op_sel_hi:[1,0]
	v_add_f32_e32 v2, v72, v2
	v_pk_mul_f32 v[80:81], v[80:81], v[148:149]
	v_pk_mul_f32 v[78:79], v[10:11], v[10:11]
	v_add_f32_e32 v2, v73, v2
	v_pk_mul_f32 v[14:15], v[80:81], s[30:31] op_sel_hi:[1,0]
	v_add_f32_e32 v2, v78, v2
	v_pk_mul_f32 v[62:63], v[62:63], v[146:147]
	v_pk_mul_f32 v[80:81], v[14:15], v[14:15]
	v_add_f32_e32 v2, v79, v2
	v_pk_mul_f32 v[18:19], v[62:63], s[30:31] op_sel_hi:[1,0]
	v_add_f32_e32 v2, v80, v2
	v_pk_mul_f32 v[64:65], v[64:65], v[142:143]
	v_pk_mul_f32 v[62:63], v[18:19], v[18:19]
	v_add_f32_e32 v2, v81, v2
	v_pk_mul_f32 v[20:21], v[64:65], s[30:31] op_sel_hi:[1,0]
	v_add_f32_e32 v2, v62, v2
	v_pk_mul_f32 v[74:75], v[74:75], v[138:139]
	v_pk_mul_f32 v[64:65], v[20:21], v[20:21]
	v_add_f32_e32 v2, v63, v2
	v_pk_mul_f32 v[90:91], v[74:75], s[30:31] op_sel_hi:[1,0]
	v_add_f32_e32 v2, v64, v2
	v_pk_mul_f32 v[76:77], v[76:77], v[134:135]
	v_pk_mul_f32 v[74:75], v[90:91], v[90:91]
	v_add_f32_e32 v2, v65, v2
	v_pk_mul_f32 v[92:93], v[76:77], s[30:31] op_sel_hi:[1,0]
	v_add_f32_e32 v2, v74, v2
	v_pk_mul_f32 v[58:59], v[58:59], v[130:131]
	v_pk_mul_f32 v[76:77], v[92:93], v[92:93]
	v_add_f32_e32 v2, v75, v2
	v_pk_mul_f32 v[94:95], v[58:59], s[30:31] op_sel_hi:[1,0]
	v_add_f32_e32 v2, v76, v2
	v_pk_mul_f32 v[60:61], v[60:61], v[126:127]
	v_pk_mul_f32 v[58:59], v[94:95], v[94:95]
	v_add_f32_e32 v2, v77, v2
	v_pk_mul_f32 v[98:99], v[60:61], s[30:31] op_sel_hi:[1,0]
	v_add_f32_e32 v2, v58, v2
	v_pk_mul_f32 v[54:55], v[54:55], v[122:123]
	v_pk_mul_f32 v[60:61], v[98:99], v[98:99]
	v_add_f32_e32 v2, v59, v2
	v_pk_mul_f32 v[30:31], v[54:55], s[30:31] op_sel_hi:[1,0]
	v_add_f32_e32 v2, v60, v2
	v_pk_mul_f32 v[56:57], v[56:57], v[118:119]
	v_pk_mul_f32 v[54:55], v[30:31], v[30:31]
	v_add_f32_e32 v2, v61, v2
	v_pk_mul_f32 v[32:33], v[56:57], s[30:31] op_sel_hi:[1,0]
	v_add_f32_e32 v2, v54, v2
	v_pk_mul_f32 v[50:51], v[50:51], v[114:115]
	v_pk_mul_f32 v[56:57], v[32:33], v[32:33]
	v_add_f32_e32 v2, v55, v2
	v_pk_mul_f32 v[82:83], v[50:51], s[30:31] op_sel_hi:[1,0]
	v_add_f32_e32 v2, v56, v2
	v_pk_mul_f32 v[50:51], v[82:83], v[82:83]
	v_add_f32_e32 v2, v57, v2
	v_pk_mul_f32 v[84:85], v[52:53], s[30:31] op_sel_hi:[1,0]
	v_add_f32_e32 v2, v50, v2
	v_pk_mul_f32 v[52:53], v[84:85], v[84:85]
	v_add_f32_e32 v2, v51, v2
	v_pk_mul_f32 v[16:17], v[16:17], s[30:31] op_sel_hi:[1,0]
	v_add_f32_e32 v2, v52, v2
	v_lshlrev_b32_e32 v150, 3, v159
	v_pk_mul_f32 v[66:67], v[16:17], v[16:17]
	v_add_f32_e32 v2, v53, v2
	v_ashrrev_i32_e32 v151, 31, v150
	v_add_f32_e32 v50, v66, v2
	s_waitcnt vmcnt(0)
	v_max_f32_e64 v2, |v110|, |v110|
	v_max_f32_e64 v3, |v49|, |v49|
	v_lshlrev_b64 v[152:153], 1, v[150:151]
	v_max_f32_e32 v49, v3, v2
	v_lshl_add_u64 v[2:3], s[20:21], 0, v[152:153]
	v_pk_mul_f32 v[8:9], v[42:43], s[30:31] op_sel_hi:[1,0]
	s_barrier
; #define LAS __attribute__((address_space(3)))
; #define MFMA32(a, b, c) __builtin_amdgcn_mfma_f32_32x32x16_bf16((a), (b), (c), 0, 0, 0)
; __device__ __forceinline__ void attn_unit(CArgs a, int layer, int unit, LAS unsigned char* lds) {
;     ...
;         const float* khn = a->mla_khn + layer * 96;
;         float gm = fmaxf(fabsf(khn[lane]), fabsf(khn[64 + (lane & 31)]));
; #pragma unroll
;         for (int o = 1; o < 64; o <<= 1) gm = fmaxf(gm, __shfl_xor(gm, o));
;         mref = 1.02f * sqrtf(qn2) * 9.797958971f * gm;
;     }
;     u32x4 kr0, kr1, vr;
;     const int kc0 = tid, kc1 = tid + 512;
;     constexpr int NT = SEQ / 64;
;     auto gloadK = [&](int t) {
;         const bf16_t* kt = Kg + (size_t)t * 64 * 96;
;         kr0 = *(const u32x4*)(kt + kc0 * 8);
;         kr1 = *(const u32x4*)(kt + (kc1 < 768 ? kc1 : 767) * 8);
;     };
;     auto gloadV = [&](int t) { vr = *(const u32x4*)(Vg + (size_t)t * 64 * 64 + tid * 8); };
;     auto lstoreK = [&](int buf) {
;         LAS bf16_t* Kl = (LAS bf16_t*)(lds + AT_K + buf * AT_KB);
;         *(LAS u32x4*)(Kl + (kc0 / 12) * AT_KLD + (kc0 % 12) * 8) = kr0;
;         if (kc1 < 768) *(LAS u32x4*)(Kl + (kc1 / 12) * AT_KLD + (kc1 % 12) * 8) = kr1;
;     };
;     auto lstoreV = [&](int buf) {
;         LAS bf16_t* Vl = (LAS bf16_t*)(lds + AT_V + buf * AT_VB);
;         *(LAS u32x4*)(Vl + (tid >> 3) * AT_VLD + (tid & 7) * 8) = vr;
;     };
;     f32x16 negm;
; #pragma unroll
;     for (int r = 0; r < 16; ++r) negm[r] = -mref;
;     auto qk = [&](int buf, f32x16& p0, f32x16& p1) {
;         const LAS bf16_t* Kl = (const LAS bf16_t*)(lds + AT_K + buf * AT_KB);
; #pragma unroll
;         for (int s = 0; s < 6; ++s) {
;             const bf16x8 k0 = *(const LAS bf16x8*)(Kl + r32 * AT_KLD + 16 * s + 8 * hi);
;             const bf16x8 k1 = *(const LAS bf16x8*)(Kl + (32 + r32) * AT_KLD + 16 * s + 8 * hi);
;             if (s == 0) { p0 = MFMA32(k0, qf[0], negm); p1 = MFMA32(k1, qf[0], negm); }
;             else { p0 = MFMA32(k0, qf[s], p0); p1 = MFMA32(k1, qf[s], p1); }
;         }
;     };
;     __syncthreads();
;     gloadK(0); gloadV(0); lstoreK(0); lstoreV(0); gloadK(1); lstoreK(1);
;     __syncthreads();
	v_xor_b32_e32 v2, 1, v247
	v_cmp_lt_i32_e32 vcc, v2, v48
	v_pk_mul_f32 v[46:47], v[86:87], v[86:87]
	v_add_f32_e32 v50, v67, v50
	v_cndmask_b32_e32 v2, v247, v2, vcc
	v_lshlrev_b32_e32 v163, 2, v2
	v_lshl_add_u64 v[2:3], s[18:19], 0, v[152:153]
	ds_bpermute_b32 v51, v163, v49
	v_add_f32_e32 v46, v46, v50
	v_add_f32_e32 v46, v47, v46
	v_xor_b32_e32 v47, 2, v247
	v_pk_mul_f32 v[40:41], v[96:97], v[96:97]
	v_cmp_lt_i32_e32 vcc, v47, v48
	v_add_f32_e32 v40, v40, v46
	s_waitcnt lgkmcnt(0)
	v_max_f32_e32 v46, v51, v51
	v_cndmask_b32_e32 v47, v247, v47, vcc
	v_max_f32_e32 v46, v49, v46
	v_lshlrev_b32_e32 v47, 2, v47
	v_pk_mul_f32 v[34:35], v[100:101], v[100:101]
	ds_bpermute_b32 v47, v47, v46
	v_add_f32_e32 v40, v41, v40
	v_pk_mul_f32 v[6:7], v[102:103], s[30:31] op_sel_hi:[1,0]
	v_add_f32_e32 v34, v34, v40
	v_pk_mul_f32 v[36:37], v[6:7], v[6:7]
	v_add_f32_e32 v34, v35, v34
	v_add_f32_e32 v34, v36, v34
	v_xor_b32_e32 v36, 4, v247
	v_cmp_lt_i32_e32 vcc, v36, v48
	s_waitcnt lgkmcnt(0)
	v_max_f32_e32 v35, v47, v47
	v_max_f32_e32 v35, v46, v35
	v_cndmask_b32_e32 v36, v247, v36, vcc
	v_lshlrev_b32_e32 v36, 2, v36
	ds_bpermute_b32 v36, v36, v35
	v_pk_mul_f32 v[38:39], v[8:9], v[8:9]
	v_add_f32_e32 v34, v37, v34
	v_pk_mul_f32 v[12:13], v[104:105], s[30:31] op_sel_hi:[1,0]
	v_add_f32_e32 v34, v38, v34
	s_waitcnt lgkmcnt(0)
	v_max_f32_e32 v36, v36, v36
	v_max_f32_e32 v35, v35, v36
	v_xor_b32_e32 v36, 8, v247
	v_cmp_lt_i32_e32 vcc, v36, v48
	v_pk_mul_f32 v[102:103], v[12:13], v[12:13]
	v_add_f32_e32 v34, v39, v34
	v_cndmask_b32_e32 v36, v247, v36, vcc
	v_lshlrev_b32_e32 v36, 2, v36
	v_pk_mul_f32 v[88:89], v[106:107], s[30:31] op_sel_hi:[1,0]
	v_add_f32_e32 v34, v102, v34
	ds_bpermute_b32 v36, v36, v35
	v_pk_mul_f32 v[104:105], v[88:89], v[88:89]
	v_add_f32_e32 v34, v103, v34
	v_add_f32_e32 v34, v104, v34
	v_add_f32_e32 v34, v105, v34
	ds_bpermute_b32 v37, v164, v34
	s_waitcnt lgkmcnt(1)
	v_max_f32_e32 v36, v36, v36
	v_max_f32_e32 v36, v35, v36
	v_xor_b32_e32 v35, 16, v247
	v_cmp_lt_i32_e32 vcc, v35, v48
	s_waitcnt lgkmcnt(0)
	v_add_f32_e32 v34, v34, v37
	s_mov_b32 s2, 0xf800000
	v_cndmask_b32_e32 v35, v247, v35, vcc
	v_lshlrev_b32_e32 v35, 2, v35
	ds_bpermute_b32 v38, v35, v36
	v_mul_f32_e32 v35, 0x4f800000, v34
	v_cmp_gt_f32_e32 vcc, s2, v34
	s_mov_b32 s3, 0x2aaaaaab
	s_movk_i32 s2, 0xd0
	v_cndmask_b32_e32 v34, v34, v35, vcc
	v_sqrt_f32_e32 v35, v34
	s_waitcnt lgkmcnt(0)
	v_max_f32_e32 v37, v38, v38
	v_max_f32_e32 v36, v36, v37
	ds_bpermute_b32 v38, v164, v36
	v_add_u32_e32 v37, -1, v35
	v_fma_f32 v39, -v37, v35, v34
	v_cmp_ge_f32_e64 s[42:43], 0, v39
	v_add_u32_e32 v39, 1, v35
	v_fma_f32 v40, -v39, v35, v34
	v_cmp_lt_f32_e64 s[44:45], 0, v40
	v_add_u32_e32 v40, 0x200, v159
	v_min_i32_e32 v41, 0x2ff, v40
	v_lshlrev_b32_e32 v154, 3, v41
	v_mul_hi_i32 v41, v159, s3
	v_lshrrev_b32_e32 v46, 31, v41
	v_ashrrev_i32_e32 v41, 1, v41
	v_add_u32_e32 v41, v41, v46
	v_mul_lo_u32 v46, v41, s2
	v_mul_lo_u32 v41, v41, 12
	v_sub_u32_e32 v41, v159, v41
	v_add_u32_e32 v46, 0, v46
	v_lshlrev_b32_e32 v41, 4, v41
	s_movk_i32 s2, 0xff
	v_add_u32_e32 v166, v46, v41
	v_cmp_lt_i32_e64 s[46:47], s2, v159
	s_movk_i32 s2, 0x100
	v_mul_hi_i32 v41, v40, s3
	v_ashrrev_i32_e32 v155, 31, v154
	ds_write_b128 v166, v[204:207]
	v_cmp_gt_i32_e64 s[40:41], s2, v159
	v_lshrrev_b32_e32 v42, 31, v41
	v_ashrrev_i32_e32 v41, 1, v41
	s_and_saveexec_b64 s[2:3], s[40:41]
	s_cbranch_execz .LBB0_68
	v_add_u32_e32 v43, v41, v42
	s_movk_i32 s12, 0xd0
	v_mul_lo_u32 v48, v43, s12
	v_mul_lo_u32 v43, v43, 12
	v_sub_u32_e32 v43, v40, v43
	v_lshlrev_b32_e32 v43, 4, v43
	v_add3_u32 v43, 0, v48, v43
	ds_write_b128 v43, v[224:227]
.LBB0_68:
	s_or_b64 exec, exec, s[2:3]
	v_lshrrev_b32_e32 v43, 3, v159
	v_and_b32_e32 v44, 56, v150
	v_mul_lo_u32 v43, v43, s82
	v_lshlrev_b32_e32 v44, 1, v44
	s_add_u32 s24, s20, 0x3000
	v_add3_u32 v167, 0, v43, v44
	s_addc_u32 s25, s21, 0
	ds_write_b128 v167, v[208:211] offset:26624
	ds_write_b128 v166, v[228:231] offset:13312
	s_and_saveexec_b64 s[2:3], s[46:47]
	s_xor_b64 s[2:3], exec, s[2:3]
	s_mov_b32 s12, 0xaaaaaaab
	v_mul_hi_u32 v2, v40, s12
	v_lshrrev_b32_e32 v2, 3, v2
	s_movk_i32 s12, 0xd0
	v_mul_lo_u32 v3, v2, s12
	v_mul_lo_u32 v2, v2, 12
	v_sub_u32_e32 v2, v40, v2
	v_lshlrev_b32_e32 v2, 4, v2
	s_andn2_saveexec_b64 s[2:3], s[2:3]
	s_cbranch_execz .LBB0_72
	v_add_u32_e32 v2, v41, v42
	s_movk_i32 s12, 0xd0
	v_mul_lo_u32 v3, v2, s12
	v_mul_lo_u32 v2, v2, 12
	v_sub_u32_e32 v2, v40, v2
	v_lshlrev_b32_e32 v2, 4, v2
	v_add3_u32 v4, 0, v3, v2
	ds_write_b128 v4, v[232:235] offset:13312

; #define LAS __attribute__((address_space(3)))
; __device__ __forceinline__ void cvt_load(const CvtDesc& d, float (&wv)[32], int lane) {
;     if (d.W) {
; #pragma unroll
;         for (int i = 0; i < 32; ++i) { const int kk = 2 * i + (lane >> 5); wv[i] = __builtin_nontemporal_load(d.W + (size_t)(d.k0 + kk) * d.N + d.srccol + (lane & 31)); }
;     } else {
; #pragma unroll
;         for (int i = 0; i < 32; ++i) wv[i] = 0.f;
;     }
; }
; __device__ __forceinline__ void cvt_store(const unsigned char* WSB, const CvtDesc& d, const float (&wv)[32], LAS float* scr, int lane) {
; #pragma unroll
;     for (int i = 0; i < 32; ++i) scr[(2 * i + (lane >> 5)) * 33 + (lane & 31)] = wv[i];
;     const int c = lane & 7;
.Lmcv_go:
	s_load_dwordx2 s[88:89], s[6:7], 0xe8
	v_readfirstlane_b32 s2, v244
	v_and_b32_e32 v2, 63, v244
	v_lshrrev_b32_e32 v3, 4, v2
	v_and_b32_e32 v4, 15, v2
	v_lshlrev_b32_e32 v4, 3, v4
	s_lshr_b32 s2, s2, 6
	s_lshl_b32 s3, s2, 14
	v_mul_u32_u24_e32 v5, 0x84, v3
	v_add3_u32 v5, v5, v4, s3
	v_and_b32_e32 v7, 7, v2
	v_lshrrev_b32_e32 v8, 3, v2
	v_mul_u32_u24_e32 v6, 0x420, v7
	v_lshl_add_u32 v6, v8, 2, v6
	v_add_u32_e32 v6, s3, v6
	v_lshlrev_b32_e32 v9, 4, v7
	v_lshlrev_b32_e32 v7, 5, v7
	s_waitcnt lgkmcnt(0)
	s_and_b32 s89, s89, 0xffff
	s_mov_b32 s90, s62
	s_mov_b32 s91, s63
	s_lshr_b32 s17, s64, 1
	s_sub_u32 s16, s16, s17
	s_lshl_b32 s16, s16, 3
	s_add_u32 s10, s16, s2
	s_sub_u32 s11, s64, s17
	s_lshl_b32 s11, s11, 3
	s_cmp_lt_u32 s10, s12
	s_cbranch_scc0 .Lmcv_rd_s
	s_mov_b32 s20, 1
	s_cmp_eq_u32 s13, 2
	s_cbranch_scc1 .Lmcv_t2_1
	s_cmpk_lt_u32 s10, 0xb00
	s_cbranch_scc0 .Lmcv_d_1
	s_mul_hi_u32 s2, s10, 0x1745d18
	s_mul_i32 s3, s2, 0xb0
	s_sub_u32 s3, s10, s3
	s_lshr_b32 s48, s3, 3
	s_and_b32 s49, s3, 3
	s_lshl_b32 s50, s48, 7
	s_lshl_b32 s49, s49, 5
	s_add_u32 s50, s50, s49
	s_lshl_b32 s51, s3, 5
	s_lshl_b32 s2, s2, 6
	s_bfe_u32 s3, s3, 0x10002
	s_lshl_b32 s3, s3, 3
	s_cmp_eq_u32 s13, 1
	s_cselect_b32 s17, 0xc8, 24
	s_add_u32 s17, s17, s3
	s_cmp_eq_u32 s13, 1
	s_cselect_b32 s48, 0xc0, 16
	s_mov_b32 s21, 0x600000
	s_cselect_b32 s21, 0x26a0000, s21
	s_mov_b32 s18, 0xb00000
	s_lshl_b32 s49, s29, 12
	s_movk_i32 s23, 0x2c00
	s_movk_i32 s22, 0x800
	s_branch .Lmcv_com_1

; #define LAS __attribute__((address_space(3)))
; __device__ __forceinline__ void cvt_load(const CvtDesc& d, float (&wv)[32], int lane) {
;     if (d.W) {
; #pragma unroll
;         for (int i = 0; i < 32; ++i) { const int kk = 2 * i + (lane >> 5); wv[i] = __builtin_nontemporal_load(d.W + (size_t)(d.k0 + kk) * d.N + d.srccol + (lane & 31)); }
;     } else {
; #pragma unroll
;         for (int i = 0; i < 32; ++i) wv[i] = 0.f;
;     }
; }
; __device__ __forceinline__ void cvt_store(const unsigned char* WSB, const CvtDesc& d, const float (&wv)[32], LAS float* scr, int lane) {
; #pragma unroll
;     for (int i = 0; i < 32; ++i) scr[(2 * i + (lane >> 5)) * 33 + (lane & 31)] = wv[i];
;     const int c = lane & 7;
;     float g[8];
;     if (d.gain) { const f32x4 g0 = *(const f32x4*)(d.gain + d.k0 + 8 * c), g1 = *(const f32x4*)(d.gain + d.k0 + 8 * c + 4);
;         g[0] = g0[0]; g[1] = g0[1]; g[2] = g0[2]; g[3] = g0[3]; g[4] = g1[0]; g[5] = g1[1]; g[6] = g1[2]; g[7] = g1[3]; }
.Lmcv_com_1:
	s_load_dwordx2 s[40:41], s[6:7], s17
	s_cmp_eq_u32 s48, -1
	s_cselect_b32 s48, s17, s48
	s_load_dwordx2 s[42:43], s[6:7], s48
	s_mul_i32 s18, s18, s29
	s_mul_i32 s3, s2, s23
	s_lshl_b32 s19, s50, 2
	s_add_u32 s3, s3, s19
	s_add_u32 s18, s18, s3
	s_lshl_b32 s3, s2, 2
	s_cmp_eq_u32 s20, 1
	s_cselect_b32 s49, s49, 0
	s_cselect_b32 s3, s3, 0
	s_add_u32 s49, s49, s3
	s_mul_i32 s3, s51, s22
	s_add_u32 s21, s21, s3
	s_lshl_b32 s3, s2, 1
	s_add_u32 s21, s21, s3
	s_waitcnt lgkmcnt(0)
	s_add_u32 s44, s40, s18
	s_addc_u32 s45, s41, 0
	s_and_b32 s45, s45, 0xffff
	s_mov_b32 s46, s62
	s_mov_b32 s47, s63
	s_ashr_i32 s3, s49, 31
	s_add_u32 s42, s42, s49
	s_addc_u32 s43, s43, s3
	v_mad_u32_u24 v10, v3, s23, v4
	s_lshl_b32 s28, s23, 2
	s_mov_b32 s19, 0
	buffer_load_dwordx2 v[32:33], v10, s[44:47], s19 offen nt
	s_add_u32 s19, s19, s28
	buffer_load_dwordx2 v[34:35], v10, s[44:47], s19 offen nt
	s_add_u32 s19, s19, s28
	buffer_load_dwordx2 v[36:37], v10, s[44:47], s19 offen nt
	s_add_u32 s19, s19, s28
	buffer_load_dwordx2 v[38:39], v10, s[44:47], s19 offen nt
	s_add_u32 s19, s19, s28
	buffer_load_dwordx2 v[40:41], v10, s[44:47], s19 offen nt
	s_add_u32 s19, s19, s28
	buffer_load_dwordx2 v[42:43], v10, s[44:47], s19 offen nt
	s_add_u32 s19, s19, s28
	buffer_load_dwordx2 v[44:45], v10, s[44:47], s19 offen nt
	s_add_u32 s19, s19, s28
	buffer_load_dwordx2 v[46:47], v10, s[44:47], s19 offen nt
	s_add_u32 s19, s19, s28
	buffer_load_dwordx2 v[48:49], v10, s[44:47], s19 offen nt
	s_add_u32 s19, s19, s28
	buffer_load_dwordx2 v[50:51], v10, s[44:47], s19 offen nt
	s_add_u32 s19, s19, s28
	buffer_load_dwordx2 v[52:53], v10, s[44:47], s19 offen nt
	s_add_u32 s19, s19, s28
	buffer_load_dwordx2 v[54:55], v10, s[44:47], s19 offen nt
	s_add_u32 s19, s19, s28
	buffer_load_dwordx2 v[56:57], v10, s[44:47], s19 offen nt
	s_add_u32 s19, s19, s28
	buffer_load_dwordx2 v[58:59], v10, s[44:47], s19 offen nt
	s_add_u32 s19, s19, s28
	buffer_load_dwordx2 v[60:61], v10, s[44:47], s19 offen nt
	s_add_u32 s19, s19, s28
	buffer_load_dwordx2 v[62:63], v10, s[44:47], s19 offen nt
	global_load_dwordx4 v[96:99], v7, s[42:43]
	global_load_dwordx4 v[100:103], v7, s[42:43] offset:16

; #define LAS __attribute__((address_space(3)))
; __device__ __forceinline__ void cvt_load(const CvtDesc& d, float (&wv)[32], int lane) {
;     if (d.W) {
; #pragma unroll
;         for (int i = 0; i < 32; ++i) { const int kk = 2 * i + (lane >> 5); wv[i] = __builtin_nontemporal_load(d.W + (size_t)(d.k0 + kk) * d.N + d.srccol + (lane & 31)); }
;     } else {
; #pragma unroll
;         for (int i = 0; i < 32; ++i) wv[i] = 0.f;
;     }
; }
; __device__ __forceinline__ void cvt_store(const unsigned char* WSB, const CvtDesc& d, const float (&wv)[32], LAS float* scr, int lane) {
; #pragma unroll
;     for (int i = 0; i < 32; ++i) scr[(2 * i + (lane >> 5)) * 33 + (lane & 31)] = wv[i];
;     const int c = lane & 7;
;     float g[8];
;     if (d.gain) { const f32x4 g0 = *(const f32x4*)(d.gain + d.k0 + 8 * c), g1 = *(const f32x4*)(d.gain + d.k0 + 8 * c + 4);
;         g[0] = g0[0]; g[1] = g0[1]; g[2] = g0[2]; g[3] = g0[3]; g[4] = g1[0]; g[5] = g1[1]; g[6] = g1[2]; g[7] = g1[3]; }
;     else {
; #pragma unroll
;         for (int e = 0; e < 8; ++e) g[e] = 1.f;
.Lmcv_com_2:
	s_load_dwordx2 s[40:41], s[6:7], s17
	s_cmp_eq_u32 s48, -1
	s_cselect_b32 s48, s17, s48
	s_load_dwordx2 s[42:43], s[6:7], s48
	s_mul_i32 s18, s18, s29
	s_mul_i32 s3, s2, s23
	s_lshl_b32 s19, s50, 2
	s_add_u32 s3, s3, s19
	s_add_u32 s18, s18, s3
	s_lshl_b32 s3, s2, 2
	s_cmp_eq_u32 s24, 1
	s_cselect_b32 s49, s49, 0
	s_cselect_b32 s3, s3, 0
	s_add_u32 s49, s49, s3
	s_mul_i32 s3, s51, s26
	s_add_u32 s25, s25, s3
	s_lshl_b32 s3, s2, 1
	s_add_u32 s25, s25, s3
	s_waitcnt lgkmcnt(0)
	s_add_u32 s44, s40, s18
	s_addc_u32 s45, s41, 0
	s_and_b32 s45, s45, 0xffff
	s_mov_b32 s46, s62
	s_mov_b32 s47, s63
	s_ashr_i32 s3, s49, 31
	s_add_u32 s42, s42, s49
	s_addc_u32 s43, s43, s3
	v_mad_u32_u24 v10, v3, s23, v4
	s_lshl_b32 s28, s23, 2
	s_mov_b32 s19, 0
	buffer_load_dwordx2 v[64:65], v10, s[44:47], s19 offen nt
	s_add_u32 s19, s19, s28
	buffer_load_dwordx2 v[66:67], v10, s[44:47], s19 offen nt
	s_add_u32 s19, s19, s28
	buffer_load_dwordx2 v[68:69], v10, s[44:47], s19 offen nt
	s_add_u32 s19, s19, s28
	buffer_load_dwordx2 v[70:71], v10, s[44:47], s19 offen nt
	s_add_u32 s19, s19, s28
	buffer_load_dwordx2 v[72:73], v10, s[44:47], s19 offen nt
	s_add_u32 s19, s19, s28
	buffer_load_dwordx2 v[74:75], v10, s[44:47], s19 offen nt
	s_add_u32 s19, s19, s28
	buffer_load_dwordx2 v[76:77], v10, s[44:47], s19 offen nt
	s_add_u32 s19, s19, s28
	buffer_load_dwordx2 v[78:79], v10, s[44:47], s19 offen nt
	s_add_u32 s19, s19, s28
	buffer_load_dwordx2 v[80:81], v10, s[44:47], s19 offen nt
	s_add_u32 s19, s19, s28
	buffer_load_dwordx2 v[82:83], v10, s[44:47], s19 offen nt
	s_add_u32 s19, s19, s28
	buffer_load_dwordx2 v[84:85], v10, s[44:47], s19 offen nt
	s_add_u32 s19, s19, s28
	buffer_load_dwordx2 v[86:87], v10, s[44:47], s19 offen nt
	s_add_u32 s19, s19, s28
	buffer_load_dwordx2 v[88:89], v10, s[44:47], s19 offen nt
	s_add_u32 s19, s19, s28
	buffer_load_dwordx2 v[90:91], v10, s[44:47], s19 offen nt
	s_add_u32 s19, s19, s28
	buffer_load_dwordx2 v[92:93], v10, s[44:47], s19 offen nt
	s_add_u32 s19, s19, s28
	buffer_load_dwordx2 v[94:95], v10, s[44:47], s19 offen nt
	global_load_dwordx4 v[104:107], v7, s[42:43]
	global_load_dwordx4 v[108:111], v7, s[42:43] offset:16
	s_waitcnt vmcnt(18)
	ds_write_b32 v5, v32 offset:0
	ds_write_b32 v5, v33 offset:4
	ds_write_b32 v5, v34 offset:528
	ds_write_b32 v5, v35 offset:532
	ds_write_b32 v5, v36 offset:1056
	ds_write_b32 v5, v37 offset:1060
	ds_write_b32 v5, v38 offset:1584
	ds_write_b32 v5, v39 offset:1588
	ds_write_b32 v5, v40 offset:2112
	ds_write_b32 v5, v41 offset:2116
	ds_write_b32 v5, v42 offset:2640
	ds_write_b32 v5, v43 offset:2644
	ds_write_b32 v5, v44 offset:3168
	ds_write_b32 v5, v45 offset:3172
	ds_write_b32 v5, v46 offset:3696
	ds_write_b32 v5, v47 offset:3700
	ds_write_b32 v5, v48 offset:4224
	ds_write_b32 v5, v49 offset:4228
	ds_write_b32 v5, v50 offset:4752
	ds_write_b32 v5, v51 offset:4756
	ds_write_b32 v5, v52 offset:5280
	ds_write_b32 v5, v53 offset:5284
	ds_write_b32 v5, v54 offset:5808
	ds_write_b32 v5, v55 offset:5812
	ds_write_b32 v5, v56 offset:6336
	ds_write_b32 v5, v57 offset:6340
	ds_write_b32 v5, v58 offset:6864
	ds_write_b32 v5, v59 offset:6868
	ds_write_b32 v5, v60 offset:7392
	ds_write_b32 v5, v61 offset:7396
	ds_write_b32 v5, v62 offset:7920
	ds_write_b32 v5, v63 offset:7924
	s_bitcmp1_b32 s20, 0
	s_cbranch_scc1 .Lmcv_hg_3
	v_mov_b32_e32 v96, 1.0
	v_mov_b32_e32 v97, 1.0
	v_mov_b32_e32 v98, 1.0
	v_mov_b32_e32 v99, 1.0
	v_mov_b32_e32 v100, 1.0
	v_mov_b32_e32 v101, 1.0
	v_mov_b32_e32 v102, 1.0
	v_mov_b32_e32 v103, 1.0

; #define LAS __attribute__((address_space(3)))
; __device__ __forceinline__ void cvt_load(const CvtDesc& d, float (&wv)[32], int lane) {
;     if (d.W) {
; #pragma unroll
;         for (int i = 0; i < 32; ++i) { const int kk = 2 * i + (lane >> 5); wv[i] = __builtin_nontemporal_load(d.W + (size_t)(d.k0 + kk) * d.N + d.srccol + (lane & 31)); }
;     } else {
; #pragma unroll
;         for (int i = 0; i < 32; ++i) wv[i] = 0.f;
;     }
; }
; __device__ __forceinline__ void cvt_store(const unsigned char* WSB, const CvtDesc& d, const float (&wv)[32], LAS float* scr, int lane) {
; #pragma unroll
;     for (int i = 0; i < 32; ++i) scr[(2 * i + (lane >> 5)) * 33 + (lane & 31)] = wv[i];
;     const int c = lane & 7;
;     float g[8];
;     if (d.gain) { const f32x4 g0 = *(const f32x4*)(d.gain + d.k0 + 8 * c), g1 = *(const f32x4*)(d.gain + d.k0 + 8 * c + 4);
;         g[0] = g0[0]; g[1] = g0[1]; g[2] = g0[2]; g[3] = g0[3]; g[4] = g1[0]; g[5] = g1[1]; g[6] = g1[2]; g[7] = g1[3]; }
;     else {
; #pragma unroll
;         for (int e = 0; e < 8; ++e) g[e] = 1.f;
.Lmcv_com_4:
	s_load_dwordx2 s[40:41], s[6:7], s17
	s_cmp_eq_u32 s48, -1
	s_cselect_b32 s48, s17, s48
	s_load_dwordx2 s[42:43], s[6:7], s48
	s_mul_i32 s18, s18, s29
	s_mul_i32 s3, s2, s23
	s_lshl_b32 s19, s50, 2
	s_add_u32 s3, s3, s19
	s_add_u32 s18, s18, s3
	s_lshl_b32 s3, s2, 2
	s_cmp_eq_u32 s20, 1
	s_cselect_b32 s49, s49, 0
	s_cselect_b32 s3, s3, 0
	s_add_u32 s49, s49, s3
	s_mul_i32 s3, s51, s22
	s_add_u32 s21, s21, s3
	s_lshl_b32 s3, s2, 1
	s_add_u32 s21, s21, s3
	s_waitcnt lgkmcnt(0)
	s_add_u32 s44, s40, s18
	s_addc_u32 s45, s41, 0
	s_and_b32 s45, s45, 0xffff
	s_mov_b32 s46, s62
	s_mov_b32 s47, s63
	s_ashr_i32 s3, s49, 31
	s_add_u32 s42, s42, s49
	s_addc_u32 s43, s43, s3
	v_mad_u32_u24 v10, v3, s23, v4
	s_lshl_b32 s28, s23, 2
	s_mov_b32 s19, 0
	buffer_load_dwordx2 v[32:33], v10, s[44:47], s19 offen nt
	s_add_u32 s19, s19, s28
	buffer_load_dwordx2 v[34:35], v10, s[44:47], s19 offen nt
	s_add_u32 s19, s19, s28
	buffer_load_dwordx2 v[36:37], v10, s[44:47], s19 offen nt
	s_add_u32 s19, s19, s28
	buffer_load_dwordx2 v[38:39], v10, s[44:47], s19 offen nt
	s_add_u32 s19, s19, s28
	buffer_load_dwordx2 v[40:41], v10, s[44:47], s19 offen nt
	s_add_u32 s19, s19, s28
	buffer_load_dwordx2 v[42:43], v10, s[44:47], s19 offen nt
	s_add_u32 s19, s19, s28
	buffer_load_dwordx2 v[44:45], v10, s[44:47], s19 offen nt
	s_add_u32 s19, s19, s28
	buffer_load_dwordx2 v[46:47], v10, s[44:47], s19 offen nt
	s_add_u32 s19, s19, s28
	buffer_load_dwordx2 v[48:49], v10, s[44:47], s19 offen nt
	s_add_u32 s19, s19, s28
	buffer_load_dwordx2 v[50:51], v10, s[44:47], s19 offen nt
	s_add_u32 s19, s19, s28
	buffer_load_dwordx2 v[52:53], v10, s[44:47], s19 offen nt
	s_add_u32 s19, s19, s28
	buffer_load_dwordx2 v[54:55], v10, s[44:47], s19 offen nt
	s_add_u32 s19, s19, s28
	buffer_load_dwordx2 v[56:57], v10, s[44:47], s19 offen nt
	s_add_u32 s19, s19, s28
	buffer_load_dwordx2 v[58:59], v10, s[44:47], s19 offen nt
	s_add_u32 s19, s19, s28
	buffer_load_dwordx2 v[60:61], v10, s[44:47], s19 offen nt
	s_add_u32 s19, s19, s28
	buffer_load_dwordx2 v[62:63], v10, s[44:47], s19 offen nt
	global_load_dwordx4 v[96:99], v7, s[42:43]
	global_load_dwordx4 v[100:103], v7, s[42:43] offset:16
	s_waitcnt vmcnt(18)
	ds_write_b32 v5, v64 offset:0
	ds_write_b32 v5, v65 offset:4
	ds_write_b32 v5, v66 offset:528
	ds_write_b32 v5, v67 offset:532
	ds_write_b32 v5, v68 offset:1056
	ds_write_b32 v5, v69 offset:1060
	ds_write_b32 v5, v70 offset:1584
	ds_write_b32 v5, v71 offset:1588
	ds_write_b32 v5, v72 offset:2112
	ds_write_b32 v5, v73 offset:2116
	ds_write_b32 v5, v74 offset:2640
	ds_write_b32 v5, v75 offset:2644
	ds_write_b32 v5, v76 offset:3168
	ds_write_b32 v5, v77 offset:3172
	ds_write_b32 v5, v78 offset:3696
	ds_write_b32 v5, v79 offset:3700
	ds_write_b32 v5, v80 offset:4224
	ds_write_b32 v5, v81 offset:4228
	ds_write_b32 v5, v82 offset:4752
	ds_write_b32 v5, v83 offset:4756
	ds_write_b32 v5, v84 offset:5280
	ds_write_b32 v5, v85 offset:5284
	ds_write_b32 v5, v86 offset:5808
	ds_write_b32 v5, v87 offset:5812
	ds_write_b32 v5, v88 offset:6336
	ds_write_b32 v5, v89 offset:6340
	ds_write_b32 v5, v90 offset:6864
	ds_write_b32 v5, v91 offset:6868
	ds_write_b32 v5, v92 offset:7392
	ds_write_b32 v5, v93 offset:7396
	ds_write_b32 v5, v94 offset:7920
	ds_write_b32 v5, v95 offset:7924
	s_bitcmp1_b32 s24, 0
	s_cbranch_scc1 .Lmcv_hg_5
	v_mov_b32_e32 v104, 1.0
	v_mov_b32_e32 v105, 1.0
	v_mov_b32_e32 v106, 1.0
	v_mov_b32_e32 v107, 1.0
	v_mov_b32_e32 v108, 1.0
	v_mov_b32_e32 v109, 1.0
	v_mov_b32_e32 v110, 1.0
	v_mov_b32_e32 v111, 1.0

; __device__ __forceinline__ int ltid() { int t = threadIdx.x; asm volatile("" : "+v"(t)); return t; }
; __device__ __forceinline__ int lbid() { int t = blockIdx.x; asm volatile("" : "+s"(t)); return t; }
; #define LAS __attribute__((address_space(3)))
; __device__ __forceinline__ void cvt_load(const CvtDesc& d, float (&wv)[32], int lane) {
;     if (d.W) {
; #pragma unroll
;         for (int i = 0; i < 32; ++i) { const int kk = 2 * i + (lane >> 5); wv[i] = __builtin_nontemporal_load(d.W + (size_t)(d.k0 + kk) * d.N + d.srccol + (lane & 31)); }
;     } else {
; #pragma unroll
;         for (int i = 0; i < 32; ++i) wv[i] = 0.f;
;     }
; }
; __device__ __forceinline__ void cvt_store(const unsigned char* WSB, const CvtDesc& d, const float (&wv)[32], LAS float* scr, int lane) {
; #pragma unroll
;     for (int i = 0; i < 32; ++i) scr[(2 * i + (lane >> 5)) * 33 + (lane & 31)] = wv[i];
;     const int c = lane & 7;
; __device__ __forceinline__ void phase_convert(CArgs a, int layer, LAS unsigned char* lds, int G) {
;     const unsigned char* WSB = a->ws;
;     const int tid = ltid(), lane = tid & 63, wave = tid >> 6;
;     LAS float* scr = (LAS float*)(lds + wave * 16384);
;     const int gw = lbid() * NWAVES + wave, NGW = G * NWAVES;
;     constexpr int NIT = 2 * 16 * 176 + 2 * 44 * 32 + 16 * 144 + 4 * 24 + 2 * 32 + 32 * 32;
;     {
;         int it = gw;
;         float wv[32]; CvtDesc cur;
;         if (it < NIT) { cur = cvt_decode(a, layer, it); cvt_load(cur, wv, lane); }
; #pragma unroll 1
;         while (it < NIT) {
;             const int nxt = it + NGW;
;             float wn[32]; CvtDesc nd = cur;
;             if (nxt < NIT) { nd = cvt_decode(a, layer, nxt); cvt_load(nd, wn, lane); }
.Lmcv_l0:
	v_readlane_b32 s16, v253, 0
	s_mov_b32 s29, 0
	s_load_dwordx2 s[88:89], s[6:7], 0xe8
	v_readfirstlane_b32 s2, v244
	v_and_b32_e32 v2, 63, v244
	v_lshrrev_b32_e32 v3, 4, v2
	v_and_b32_e32 v4, 15, v2
	v_lshlrev_b32_e32 v4, 3, v4
	s_lshr_b32 s2, s2, 6
	s_lshl_b32 s3, s2, 14
	v_mul_u32_u24_e32 v5, 0x84, v3
	v_add3_u32 v5, v5, v4, s3
	v_and_b32_e32 v7, 7, v2
	v_lshrrev_b32_e32 v8, 3, v2
	v_mul_u32_u24_e32 v6, 0x420, v7
	v_lshl_add_u32 v6, v8, 2, v6
	v_add_u32_e32 v6, s3, v6
	v_lshlrev_b32_e32 v9, 4, v7
	v_lshlrev_b32_e32 v7, 5, v7
	s_waitcnt lgkmcnt(0)
	s_and_b32 s89, s89, 0xffff
	s_mov_b32 s90, s62
	s_mov_b32 s91, s63
	s_lshl_b32 s16, s16, 3
	s_add_u32 s54, s16, s2
	s_lshl_b32 s11, s64, 3
	s_mov_b32 s13, 0
	s_movk_i32 s12, 0x1080
	s_mov_b32 s10, s54
	s_cmp_lt_u32 s10, s12
	s_cbranch_scc0 .Lmcv_rd_l0
	s_mov_b32 s20, 1
	s_cmp_eq_u32 s13, 2
	s_cbranch_scc1 .Lmcv_t2_6
	s_cmpk_lt_u32 s10, 0xb00
	s_cbranch_scc0 .Lmcv_d_6
	s_mul_hi_u32 s2, s10, 0x1745d18
	s_mul_i32 s3, s2, 0xb0
	s_sub_u32 s3, s10, s3
	s_lshr_b32 s48, s3, 3
	s_and_b32 s49, s3, 3
	s_lshl_b32 s50, s48, 7
	s_lshl_b32 s49, s49, 5
	s_add_u32 s50, s50, s49
	s_lshl_b32 s51, s3, 5
	s_lshl_b32 s2, s2, 6
	s_bfe_u32 s3, s3, 0x10002
	s_lshl_b32 s3, s3, 3
	s_cmp_eq_u32 s13, 1
	s_cselect_b32 s17, 0xc8, 24
	s_add_u32 s17, s17, s3
	s_cmp_eq_u32 s13, 1
	s_cselect_b32 s48, 0xc0, 16
	s_mov_b32 s21, 0x600000
	s_cselect_b32 s21, 0x26a0000, s21
	s_mov_b32 s18, 0xb00000
	s_lshl_b32 s49, s29, 12
	s_movk_i32 s23, 0x2c00
	s_movk_i32 s22, 0x800
	s_branch .Lmcv_com_6

; __device__ __forceinline__ CvtDesc cvt_decode(CArgs a, int layer, int it) {
;     ...
;     r -= 2 * I_D;
;     if (r < I_IN) {
;         const int db = r % 144, kb = r / 144, uc = db * 32;
;         int oc;
;         if (uc < 2560) oc = uc; else if (uc < 2816) oc = 2592 + (uc - 2560); else if (uc < 2944) oc = 2848 + (uc - 2816); else if (uc < 2976) oc = 2976 + (uc - 2944);
;         else if (uc < 3008) oc = 2560 + (uc - 2976); else if (uc < 3072) oc = -1; else oc = 3008 + (uc - 3072);
;         d.W = oc >= 0 ? a->w_in + (size_t)layer * DM * DIN : nullptr; d.gain = a->mix_norm + layer * DM; d.WT = (bf16_t*)(wsw + W_IN);
;         d.N = DIN; d.K = DM; d.ld = DM; d.srccol = oc; d.destrow = uc; d.k0 = kb * 64; return d;
;     }
;     r -= I_IN;
;     if (r < I_UQ) {
;         const int db = r % 24, kb = r / 24;
;         d.W = a->mla_w_uq + (size_t)layer * 256 * 768; d.gain = a->mla_q_norm + layer * 256; d.WT = (bf16_t*)(wsw + W_UQ);
;         d.N = 768; d.K = 256; d.ld = 256; d.srccol = db * 32; d.destrow = db * 32; d.k0 = kb * 64; return d;
;     }
;     r -= I_UQ;
;     if (r < I_UKV) {
;         const int db = r % 32, kb = r / 32, pn = db >> 3, bj = (db & 7) >> 2, wc = db & 3;
;         d.W = a->mla_w_ukv + (size_t)layer * 128 * 1024; d.gain = a->mla_kv_norm + layer * 128; d.WT = (bf16_t*)(wsw + W_UKV);
;         d.N = 1024; d.K = 128; d.ld = 128; d.srccol = (pn < 2) ? (4 * pn + wc) * 128 + 32 * bj : (4 * (pn - 2) + wc) * 128 + 64 + 32 * bj; d.destrow = db * 32; d.k0 = kb * 64; return d;
;     }
;     r -= I_UKV;
;     {
;         const int db = r % 32, kb = r / 32, k0 = kb * 64;
;         d.W = a->w_out + (size_t)layer * 2048 * DM;
;         d.gain = (k0 < 1024) ? a->ssd_norm + layer * 1024 : (k0 < 1536) ? a->mla_out_norm + layer * 512 - 1024 : a->conv_out_norm + layer * 512 - 1536;
;         d.WT = (bf16_t*)(wsw + W_OUT); d.N = DM; d.K = 2048; d.ld = 2048; d.srccol = db * 32; d.destrow = db * 32; d.k0 = k0; return d;
;     }
.Lmcv_rd_l0:
	s_waitcnt vmcnt(0)
	s_mov_b32 s13, 2
	s_movk_i32 s12, 0xda0
	s_mov_b32 s10, s54
	s_cmp_lt_u32 s10, s12
	s_cbranch_scc0 .Lmcv_rd_l2
	s_mov_b32 s20, 1
	s_cmp_eq_u32 s13, 2
	s_cbranch_scc1 .Lmcv_t2_11
	s_cmpk_lt_u32 s10, 0xb00
	s_cbranch_scc0 .Lmcv_d_11
	s_mul_hi_u32 s2, s10, 0x1745d18
	s_mul_i32 s3, s2, 0xb0
	s_sub_u32 s3, s10, s3
	s_lshr_b32 s48, s3, 3
	s_and_b32 s49, s3, 3
	s_lshl_b32 s50, s48, 7
	s_lshl_b32 s49, s49, 5
	s_add_u32 s50, s50, s49
	s_lshl_b32 s51, s3, 5
	s_lshl_b32 s2, s2, 6
	s_bfe_u32 s3, s3, 0x10002
	s_lshl_b32 s3, s3, 3
	s_cmp_eq_u32 s13, 1
	s_cselect_b32 s17, 0xc8, 24
	s_add_u32 s17, s17, s3
	s_cmp_eq_u32 s13, 1
	s_cselect_b32 s48, 0xc0, 16
	s_mov_b32 s21, 0x600000
	s_cselect_b32 s21, 0x26a0000, s21
	s_mov_b32 s18, 0xb00000
	s_lshl_b32 s49, s29, 12
	s_movk_i32 s23, 0x2c00
	s_movk_i32 s22, 0x800
	s_branch .Lmcv_com_11
